# attention loop edges: softmax VALU left behind the end-of-step barrier issued before the counted wait and barrier; first QK step issues its ctab and K-fragment LDS reads before the LDS-DMA issue block
# speedup vs baseline: 1.0070x; 1.0063x over previous
; #define LAS __attribute__((address_space(3)))
; __device__ __forceinline__ void finishSM(f32x16& p0, f32x16& p1, float alpha, float& l_reg, bf16x8& pa0, bf16x8& pa1, bf16x8& pa2, bf16x8& pa3) {
; #pragma unroll
;     for (int r = 0; r < 16; ++r) p1[r] = __builtin_amdgcn_exp2f(p1[r]);
;     float ps = 0;
; #pragma unroll
;     for (int r = 0; r < 16; ++r) ps += p0[r];
; #pragma unroll
;     for (int r = 0; r < 16; ++r) ps += p1[r];
;     { auto rr = __builtin_amdgcn_permlane32_swap(__float_as_uint(ps), __float_as_uint(ps), false, false);
;       ps = __uint_as_float(rr[0]) + __uint_as_float(rr[1]); }
;     l_reg = l_reg * alpha + ps;
;     ...
;     PK4(p0, 0, pa0); PK4(p0, 8, pa1); PK4(p1, 0, pa2); PK4(p1, 8, pa3);
; __device__ __forceinline__ void qkt(f32x16& p0, f32x16& p1, const char* Kslot, int r32, int hi, const bf16x8* qr, const LAS f32x4* cp) {
; #pragma unroll
;     for (int g = 0; g < 4; ++g) { const f32x4 c0 = cp[2 * g], c1 = cp[8 + 2 * g];
; #pragma unroll
;         for (int j = 0; j < 4; ++j) { p0[4 * g + j] = c0[j]; p1[4 * g + j] = c1[j]; } }
;     const char* kb[4];
; #pragma unroll
;     for (int dd = 0; dd < 4; ++dd) kb[dd] = Kslot + KSWZ(r32, (dd * 16 + hi * 8) * 2);
; #pragma unroll
;     for (int d0 = 0; d0 < 8; ++d0) { const char* a = kb[d0 & 3] + (d0 >> 2) * 128;
;         bf16x8 b0 = *reinterpret_cast<const bf16x8*>(a);
;         bf16x8 b1 = *reinterpret_cast<const bf16x8*>(a + 32 * 256);
;         p0 = __builtin_amdgcn_mfma_f32_32x32x16_bf16(b0, qr[d0], p0, 0, 0, 0);
;         p1 = __builtin_amdgcn_mfma_f32_32x32x16_bf16(b1, qr[d0], p1, 0, 0, 0); }
; }
.LBB0_521:
	s_add_i32 s3, s73, 0
	v_add_u32_e32 v218, s3, v193
	ds_read_b128 v[80:83], v217
	ds_read_b128 v[84:87], v217 offset:32
	ds_read_b128 v[64:67], v217 offset:128
	ds_read_b128 v[68:71], v217 offset:160
	ds_read_b128 v[88:91], v217 offset:64
	ds_read_b128 v[72:75], v217 offset:192
	ds_read_b128 v[92:95], v217 offset:96
	ds_read_b128 v[76:79], v217 offset:224
	ds_read_b128 v[238:241], v218 offset:49152
	ds_read_b128 v[242:245], v218 offset:57344
	s_add_i32 s3, s71, -1
	s_cmp_lt_u32 s3, s93
	s_cselect_b64 s[88:89], -1, 0
	s_cmp_ge_u32 s3, s93
	s_cselect_b64 s[96:97], -1, 0
	s_and_b64 vcc, exec, s[96:97]
	v_lshl_add_u64 v[156:157], s[68:69], 0, v[128:129]
	v_lshl_add_u64 v[158:159], s[68:69], 0, v[148:149]
	s_cbranch_vccnz .LBB0_523
	s_add_i32 s3, s70, s72
	v_lshl_add_u64 v[250:251], v[156:157], 0, s[80:81]
	s_add_i32 m0, s3, 0xc000
	s_add_i32 s3, s3, 0xc400
	v_lshl_add_u64 v[252:253], v[158:159], 0, s[80:81]
	global_load_lds_dwordx4 v[250:251], off
	s_mov_b32 m0, s3
	s_nop 0
	global_load_lds_dwordx4 v[252:253], off
.LBB0_523:
	s_add_i32 s3, s70, s76
	v_lshl_add_u64 v[160:161], s[68:69], 0, v[150:151]
	v_lshl_add_u64 v[250:251], v[160:161], 0, s[84:85]
	s_mov_b32 m0, s3
	v_lshl_add_u64 v[162:163], s[68:69], 0, v[152:153]
	global_load_lds_dwordx4 v[250:251], off
	v_lshl_add_u64 v[250:251], v[162:163], 0, s[84:85]
	s_add_i32 m0, s3, 0x400
	s_nop 0
	global_load_lds_dwordx4 v[250:251], off
	s_add_i32 s3, s73, 0
	v_add_u32_e32 v219, s3, v194
	v_add_u32_e32 v220, s3, v195
	s_waitcnt lgkmcnt(0)
	v_mfma_f32_32x32x16_bf16 v[80:95], v[238:241], v[96:99], v[80:95]
	v_add_u32_e32 v237, s3, v196
	v_exp_f32_e32 v173, v173
	v_exp_f32_e32 v176, v176
	v_exp_f32_e32 v177, v177
	v_exp_f32_e32 v178, v178
	v_exp_f32_e32 v179, v179
	v_exp_f32_e32 v246, v165
	v_mfma_f32_32x32x16_bf16 v[64:79], v[242:245], v[96:99], v[64:79]
	ds_read_b128 v[238:241], v219 offset:49152
	ds_read_b128 v[242:245], v219 offset:57344
	s_waitcnt lgkmcnt(0)
	v_mfma_f32_32x32x16_bf16 v[64:79], v[242:245], v[100:103], v[64:79]
	v_mfma_f32_32x32x16_bf16 v[80:95], v[238:241], v[100:103], v[80:95]
	ds_read_b128 v[238:241], v220 offset:49152
	ds_read_b128 v[242:245], v220 offset:57344
	s_waitcnt lgkmcnt(0)
	v_mfma_f32_32x32x16_bf16 v[64:79], v[242:245], v[104:107], v[64:79]
	v_mfma_f32_32x32x16_bf16 v[80:95], v[238:241], v[104:107], v[80:95]
	ds_read_b128 v[238:241], v237 offset:49152
	ds_read_b128 v[242:245], v237 offset:57344
	s_waitcnt lgkmcnt(0)
	v_mfma_f32_32x32x16_bf16 v[64:79], v[242:245], v[108:111], v[64:79]
	v_mfma_f32_32x32x16_bf16 v[80:95], v[238:241], v[108:111], v[80:95]
	v_xor_b32_e32 v249, 0x80, v218
	v_xor_b32_e32 v250, 0x80, v219
	v_xor_b32_e32 v251, 0x80, v220
	v_xor_b32_e32 v252, 0x80, v237
	ds_read_b128 v[238:241], v249 offset:49152
	ds_read_b128 v[242:245], v249 offset:57344
	s_waitcnt lgkmcnt(0)
	v_mfma_f32_32x32x16_bf16 v[64:79], v[242:245], v[112:115], v[64:79]
	v_mfma_f32_32x32x16_bf16 v[80:95], v[238:241], v[112:115], v[80:95]
	ds_read_b128 v[238:241], v250 offset:49152
	ds_read_b128 v[242:245], v250 offset:57344
	s_waitcnt lgkmcnt(0)
	v_mfma_f32_32x32x16_bf16 v[64:79], v[242:245], v[116:119], v[64:79]
	v_mfma_f32_32x32x16_bf16 v[80:95], v[238:241], v[116:119], v[80:95]
	ds_read_b128 v[238:241], v251 offset:49152
	ds_read_b128 v[242:245], v251 offset:57344
	v_exp_f32_e32 v220, v168
	s_waitcnt lgkmcnt(0)
	v_mfma_f32_32x32x16_bf16 v[64:79], v[242:245], v[120:123], v[64:79]
	v_mfma_f32_32x32x16_bf16 v[80:95], v[238:241], v[120:123], v[80:95]
	ds_read_b128 v[238:241], v252 offset:49152
	ds_read_b128 v[242:245], v252 offset:57344
	v_exp_f32_e32 v237, v169
	s_waitcnt lgkmcnt(0)
	v_mfma_f32_32x32x16_bf16 v[64:79], v[242:245], v[124:127], v[64:79]
	v_exp_f32_e32 v245, v164
	v_add_f32_e32 v164, 0, v221
	v_add_f32_e32 v164, v236, v164
	v_add_f32_e32 v164, v233, v164
	v_add_f32_e32 v164, v235, v164
	v_add_f32_e32 v164, v231, v164
	v_add_f32_e32 v164, v234, v164
	v_add_f32_e32 v164, v230, v164
	v_add_f32_e32 v164, v232, v164
	v_add_f32_e32 v164, v227, v164
	v_add_f32_e32 v164, v229, v164
	v_add_f32_e32 v164, v225, v164
	v_add_f32_e32 v164, v228, v164
	v_add_f32_e32 v164, v223, v164
	v_add_f32_e32 v164, v226, v164
	v_mfma_f32_32x32x16_bf16 v[80:95], v[238:241], v[124:127], v[80:95]
	v_exp_f32_e32 v238, v172
	v_add_f32_e32 v164, v222, v164
	v_add_f32_e32 v164, v224, v164
	v_add_f32_e32 v164, v220, v164
	v_add_f32_e32 v164, v237, v164
	v_exp_f32_e32 v239, v166
	v_add_f32_e32 v164, v238, v164
	v_exp_f32_e32 v240, v167
	v_add_f32_e32 v164, v173, v164
	v_exp_f32_e32 v241, v170
	v_add_f32_e32 v164, v176, v164
	v_exp_f32_e32 v242, v171
	v_add_f32_e32 v164, v177, v164
	v_exp_f32_e32 v243, v174
	v_add_f32_e32 v164, v239, v164
	v_exp_f32_e32 v244, v175
	v_add_f32_e32 v164, v240, v164
	v_add_f32_e32 v164, v241, v164
	v_add_f32_e32 v164, v242, v164
	v_add_f32_e32 v164, v243, v164
	v_add_f32_e32 v164, v244, v164
	v_add_f32_e32 v164, v178, v164
	v_add_f32_e32 v164, v179, v164
	v_add_f32_e32 v164, v245, v164
	v_add_f32_e32 v218, v246, v164
	v_mov_b32_e32 v219, v218
	s_nop 1
	v_permlane32_swap_b32_e32 v218, v219
	v_cvt_pk_bf16_f32 v164, v221, v236
	v_cvt_pk_bf16_f32 v165, v233, v235
	v_cvt_pk_bf16_f32 v166, v231, v234
	v_cvt_pk_bf16_f32 v167, v230, v232
	v_cvt_pk_bf16_f32 v168, v227, v229
	v_cvt_pk_bf16_f32 v169, v225, v228
	v_cvt_pk_bf16_f32 v170, v223, v226
	v_cvt_pk_bf16_f32 v171, v222, v224
	v_cvt_pk_bf16_f32 v172, v220, v237
	v_cvt_pk_bf16_f32 v173, v238, v173
	v_cvt_pk_bf16_f32 v174, v176, v177
	v_cvt_pk_bf16_f32 v175, v239, v240
	v_cvt_pk_bf16_f32 v176, v241, v242
	v_cvt_pk_bf16_f32 v177, v243, v244
	v_cvt_pk_bf16_f32 v178, v178, v179
	v_cvt_pk_bf16_f32 v179, v245, v246
	s_nop 0
	v_permlane32_swap_b32_e32 v164, v166
	v_permlane32_swap_b32_e32 v165, v167
	v_permlane32_swap_b32_e32 v168, v170
	v_permlane32_swap_b32_e32 v169, v171
	v_permlane32_swap_b32_e32 v172, v174
	v_permlane32_swap_b32_e32 v173, v175
	v_permlane32_swap_b32_e32 v176, v178
	v_permlane32_swap_b32_e32 v177, v179
	v_add_u32_e32 v236, s2, v192
	s_sub_i32 s2, s92, 64
	s_cmp_le_i32 s2, s91
	s_cbranch_scc0 .Lband_0
; #define SBAR() __builtin_amdgcn_sched_barrier(0)
; #define PV_RD(d0, kh, X) do { constexpr int b_ = v_rd_off(d0, 2 * (kh), 0); TRRD(X##l0, b_); TRRD(X##h0, b_ + 2048); TRRD(X##l1, b_ + 4096); TRRD(X##h1, b_ + 6144); } while (0)
; #define PV_MM(d0, X, PA, PB) do { \
;         o[d0] = __builtin_amdgcn_mfma_f32_32x32x16_bf16(PA, (bf16x8){X##l0[0], X##l0[1], X##l0[2], X##l0[3], X##h0[0], X##h0[1], X##h0[2], X##h0[3]}, o[d0], 0, 0, 0);   \
;         o[d0] = __builtin_amdgcn_mfma_f32_32x32x16_bf16(PB, (bf16x8){X##l1[0], X##l1[1], X##l1[2], X##l1[3], X##h1[0], X##h1[1], X##h1[2], X##h1[3]}, o[d0], 0, 0, 0); } while (0)
; #define PV_W4() do { asm volatile("s_waitcnt lgkmcnt(4)" ::: "memory"); SBAR(); } while (0)
; #define PV_W0() do { asm volatile("s_waitcnt lgkmcnt(0)" ::: "memory"); SBAR(); } while (0)
; __device__ __forceinline__ void partialSM(f32x16& p0, f32x16& p1, float& m_reg, float& mn, float& alpha) {
;     float pmax = p0[0];
; #pragma unroll
;     for (int r = 1; r < 16; ++r) pmax = fmaxf(pmax, p0[r]);
; #pragma unroll
;     for (int r = 0; r < 16; ++r) pmax = fmaxf(pmax, p1[r]);
;     { auto rr = __builtin_amdgcn_permlane32_swap(__float_as_uint(pmax), __float_as_uint(pmax), false, false);
;       pmax = fmaxf(__uint_as_float(rr[0]), __uint_as_float(rr[1])); }
; __device__ __forceinline__ void pv_tile(f32x16* o, int vb0, bf16x8 pa0, bf16x8 pa1, bf16x8 pa2, bf16x8 pa3) {
;     ...
;     s16x4 al0, al1, ah0, ah1, bl0, bl1, bh0, bh1;
;     PV_RD(0, 0, a);
;     PV_RD(0, 1, b); PV_W4(); PV_MM(0, a, pa0, pa1); SBAR();
;     PV_RD(1, 0, a); PV_W4(); PV_MM(0, b, pa2, pa3); SBAR();
;     PV_RD(1, 1, b); PV_W4(); PV_MM(1, a, pa0, pa1); SBAR();
;     PV_RD(2, 0, a); PV_W4(); PV_MM(1, b, pa2, pa3); SBAR();
;     PV_RD(2, 1, b); PV_W4(); PV_MM(2, a, pa0, pa1); SBAR();
;     PV_RD(3, 0, a); PV_W4(); PV_MM(2, b, pa2, pa3); SBAR();
;     PV_RD(3, 1, b); PV_W4(); PV_MM(3, a, pa0, pa1); SBAR();
;     PV_W0(); PV_MM(3, b, pa2, pa3);
	ds_read_b64_tr_b16 v[220:221], v236 offset:0
	ds_read_b64_tr_b16 v[222:223], v236 offset:0x800
	ds_read_b64_tr_b16 v[224:225], v236 offset:0x1000
	ds_read_b64_tr_b16 v[226:227], v236 offset:0x1800
	ds_read_b64_tr_b16 v[228:229], v236 offset:0x2000
	ds_read_b64_tr_b16 v[230:231], v236 offset:0x2800
	ds_read_b64_tr_b16 v[232:233], v236 offset:0x3000
	ds_read_b64_tr_b16 v[234:235], v236 offset:0x3800
	s_waitcnt lgkmcnt(4)
	s_nop 0
	v_mfma_f32_32x32x16_bf16 v[48:63], v[164:167], v[220:223], v[48:63]
	v_max_f32_e32 v253, v81, v81
	v_max_f32_e32 v254, v80, v80
	v_mfma_f32_32x32x16_bf16 v[48:63], v[168:171], v[224:227], v[48:63]
	v_max_f32_e32 v253, v254, v253
	v_max3_f32 v253, v253, v82, v83
	ds_read_b64_tr_b16 v[220:221], v236 offset:0x200
	ds_read_b64_tr_b16 v[222:223], v236 offset:0xa00
	ds_read_b64_tr_b16 v[224:225], v236 offset:0x1200
	ds_read_b64_tr_b16 v[226:227], v236 offset:0x1a00
	s_waitcnt lgkmcnt(4)
	v_mfma_f32_32x32x16_bf16 v[48:63], v[172:175], v[228:231], v[48:63]
	v_max3_f32 v253, v253, v84, v85
	v_max3_f32 v253, v253, v86, v87
	v_mfma_f32_32x32x16_bf16 v[48:63], v[176:179], v[232:235], v[48:63]
	v_max3_f32 v253, v253, v88, v89
	v_max3_f32 v253, v253, v90, v91
	ds_read_b64_tr_b16 v[228:229], v236 offset:0x2200
	ds_read_b64_tr_b16 v[230:231], v236 offset:0x2a00
	ds_read_b64_tr_b16 v[232:233], v236 offset:0x3200
	ds_read_b64_tr_b16 v[234:235], v236 offset:0x3a00
	s_waitcnt lgkmcnt(4)
	v_mfma_f32_32x32x16_bf16 v[32:47], v[164:167], v[220:223], v[32:47]
	v_max3_f32 v253, v253, v92, v93
	v_max3_f32 v253, v253, v94, v95
	v_mfma_f32_32x32x16_bf16 v[32:47], v[168:171], v[224:227], v[32:47]
	v_max3_f32 v253, v253, v64, v65
	v_max3_f32 v253, v253, v66, v67
	ds_read_b64_tr_b16 v[220:221], v236 offset:0x400
	ds_read_b64_tr_b16 v[222:223], v236 offset:0xc00
	ds_read_b64_tr_b16 v[224:225], v236 offset:0x1400
	ds_read_b64_tr_b16 v[226:227], v236 offset:0x1c00
	s_waitcnt lgkmcnt(4)
	v_mfma_f32_32x32x16_bf16 v[32:47], v[172:175], v[228:231], v[32:47]
	v_max3_f32 v253, v253, v68, v69
	v_max3_f32 v253, v253, v70, v71
	v_mfma_f32_32x32x16_bf16 v[32:47], v[176:179], v[232:235], v[32:47]
	v_max3_f32 v253, v253, v72, v73
	v_max3_f32 v253, v253, v74, v75
	ds_read_b64_tr_b16 v[228:229], v236 offset:0x2400
	ds_read_b64_tr_b16 v[230:231], v236 offset:0x2c00
	ds_read_b64_tr_b16 v[232:233], v236 offset:0x3400
	ds_read_b64_tr_b16 v[234:235], v236 offset:0x3c00
	s_waitcnt lgkmcnt(4)
	v_mfma_f32_32x32x16_bf16 v[16:31], v[164:167], v[220:223], v[16:31]
	v_max3_f32 v253, v253, v76, v77
	v_max3_f32 v253, v253, v78, v79
	v_mfma_f32_32x32x16_bf16 v[16:31], v[168:171], v[224:227], v[16:31]
	v_mov_b32_e32 v254, v253
	s_nop 1
	ds_read_b64_tr_b16 v[220:221], v236 offset:0x600
	ds_read_b64_tr_b16 v[222:223], v236 offset:0xe00
	ds_read_b64_tr_b16 v[224:225], v236 offset:0x1600
	ds_read_b64_tr_b16 v[226:227], v236 offset:0x1e00
	s_waitcnt lgkmcnt(4)
	v_mfma_f32_32x32x16_bf16 v[16:31], v[172:175], v[228:231], v[16:31]
	v_permlane32_swap_b32_e32 v253, v254
	v_max_f32_e32 v254, v254, v254
	v_mfma_f32_32x32x16_bf16 v[16:31], v[176:179], v[232:235], v[16:31]
	v_max_f32_e32 v253, v253, v253
	v_max_f32_e32 v253, v253, v254
	ds_read_b64_tr_b16 v[228:229], v236 offset:0x2600
	ds_read_b64_tr_b16 v[230:231], v236 offset:0x2e00
	ds_read_b64_tr_b16 v[232:233], v236 offset:0x3600
	ds_read_b64_tr_b16 v[234:235], v236 offset:0x3e00
	s_waitcnt lgkmcnt(4)
	v_mfma_f32_32x32x16_bf16 v[0:15], v[164:167], v[220:223], v[0:15]
	v_sub_f32_e32 v254, v253, v154
	v_cmp_ge_f32_e32 vcc, s33, v254
	v_mfma_f32_32x32x16_bf16 v[0:15], v[168:171], v[224:227], v[0:15]
	v_max_f32_e32 v254, v154, v154
	v_max_f32_e32 v253, v254, v253
	s_waitcnt lgkmcnt(0)
	v_mfma_f32_32x32x16_bf16 v[0:15], v[172:175], v[228:231], v[0:15]
	v_sub_f32_e32 v254, v154, v253
	v_exp_f32_e32 v254, v254
	v_mfma_f32_32x32x16_bf16 v[0:15], v[176:179], v[232:235], v[0:15]
	v_mov_b32_e32 v164, v253
	v_mov_b32_e32 v165, v254
	s_branch .Lmaxtail_0

; __device__ __forceinline__ void partialSM(f32x16& p0, f32x16& p1, float& m_reg, float& mn, float& alpha) {
;     ...
;     if (__builtin_expect(__all((pmax - m_reg) <= THR2), 1)) { mn = m_reg; alpha = 1.f; }
;     else { mn = fmaxf(m_reg, pmax); alpha = __builtin_amdgcn_exp2f(m_reg - mn); m_reg = mn; }
; #pragma unroll
;     for (int r = 0; r < 16; ++r) p0[r] = p0[r] - mn;
; #pragma unroll
;     for (int r = 0; r < 16; ++r) p1[r] = p1[r] - mn;
; #pragma unroll
;     for (int r = 0; r < 16; ++r) p0[r] = __builtin_amdgcn_exp2f(p0[r]);
; }
.LBB0_529:
	v_cndmask_b32_e64 v154, v164, v154, s[2:3]
	v_pk_add_f32 v[80:81], v[80:81], v[154:155] op_sel_hi:[1,0] neg_lo:[0,1] neg_hi:[0,1]
	v_pk_add_f32 v[82:83], v[82:83], v[154:155] op_sel_hi:[1,0] neg_lo:[0,1] neg_hi:[0,1]
	v_pk_add_f32 v[84:85], v[84:85], v[154:155] op_sel_hi:[1,0] neg_lo:[0,1] neg_hi:[0,1]
	v_pk_add_f32 v[86:87], v[86:87], v[154:155] op_sel_hi:[1,0] neg_lo:[0,1] neg_hi:[0,1]
	v_pk_add_f32 v[88:89], v[88:89], v[154:155] op_sel_hi:[1,0] neg_lo:[0,1] neg_hi:[0,1]
	v_pk_add_f32 v[90:91], v[90:91], v[154:155] op_sel_hi:[1,0] neg_lo:[0,1] neg_hi:[0,1]
	v_pk_add_f32 v[92:93], v[92:93], v[154:155] op_sel_hi:[1,0] neg_lo:[0,1] neg_hi:[0,1]
	v_pk_add_f32 v[94:95], v[94:95], v[154:155] op_sel_hi:[1,0] neg_lo:[0,1] neg_hi:[0,1]
	v_pk_add_f32 v[164:165], v[64:65], v[154:155] op_sel_hi:[1,0] neg_lo:[0,1] neg_hi:[0,1]
	v_pk_add_f32 v[166:167], v[66:67], v[154:155] op_sel_hi:[1,0] neg_lo:[0,1] neg_hi:[0,1]
	v_pk_add_f32 v[168:169], v[68:69], v[154:155] op_sel_hi:[1,0] neg_lo:[0,1] neg_hi:[0,1]
	v_pk_add_f32 v[170:171], v[70:71], v[154:155] op_sel_hi:[1,0] neg_lo:[0,1] neg_hi:[0,1]
	v_pk_add_f32 v[172:173], v[72:73], v[154:155] op_sel_hi:[1,0] neg_lo:[0,1] neg_hi:[0,1]
	v_pk_add_f32 v[174:175], v[74:75], v[154:155] op_sel_hi:[1,0] neg_lo:[0,1] neg_hi:[0,1]
	v_sub_f32_e32 v176, v76, v154
	v_exp_f32_e32 v177, v80
	v_exp_f32_e32 v178, v81
	v_exp_f32_e32 v179, v82
	v_exp_f32_e32 v221, v83
	v_exp_f32_e32 v222, v84
	v_exp_f32_e32 v223, v85
	v_exp_f32_e32 v224, v86
	v_exp_f32_e32 v225, v87
	v_exp_f32_e32 v226, v88
	v_exp_f32_e32 v227, v89
	v_exp_f32_e32 v228, v90
	v_exp_f32_e32 v229, v91
	v_exp_f32_e32 v230, v92
	v_exp_f32_e32 v231, v93
	v_exp_f32_e32 v232, v94
	v_exp_f32_e32 v233, v95
	v_sub_f32_e32 v234, v77, v154
	v_sub_f32_e32 v235, v78, v154
	v_sub_f32_e32 v236, v79, v154
	s_mov_b64 s[4:5], -1
	s_and_b64 vcc, exec, s[96:97]
	s_cbranch_vccz .LBB0_531
	s_waitcnt vmcnt(2) lgkmcnt(0)
	s_barrier
	s_mov_b64 s[4:5], 0

; #define LAS __attribute__((address_space(3)))
; __device__ __forceinline__ void finishSM(f32x16& p0, f32x16& p1, float alpha, float& l_reg, bf16x8& pa0, bf16x8& pa1, bf16x8& pa2, bf16x8& pa3) {
; #pragma unroll
;     for (int r = 0; r < 16; ++r) p1[r] = __builtin_amdgcn_exp2f(p1[r]);
;     float ps = 0;
; #pragma unroll
;     for (int r = 0; r < 16; ++r) ps += p0[r];
; #pragma unroll
;     for (int r = 0; r < 16; ++r) ps += p1[r];
;     { auto rr = __builtin_amdgcn_permlane32_swap(__float_as_uint(ps), __float_as_uint(ps), false, false);
;       ps = __uint_as_float(rr[0]) + __uint_as_float(rr[1]); }
;     l_reg = l_reg * alpha + ps;
;     ...
;     PK4(p0, 0, pa0); PK4(p0, 8, pa1); PK4(p1, 0, pa2); PK4(p1, 8, pa3);
; __device__ __forceinline__ void qkt(f32x16& p0, f32x16& p1, const char* Kslot, int r32, int hi, const bf16x8* qr, const LAS f32x4* cp) {
; #pragma unroll
;     for (int g = 0; g < 4; ++g) { const f32x4 c0 = cp[2 * g], c1 = cp[8 + 2 * g];
; #pragma unroll
;         for (int j = 0; j < 4; ++j) { p0[4 * g + j] = c0[j]; p1[4 * g + j] = c1[j]; } }
;     const char* kb[4];
; #pragma unroll
;     for (int dd = 0; dd < 4; ++dd) kb[dd] = Kslot + KSWZ(r32, (dd * 16 + hi * 8) * 2);
; #pragma unroll
;     for (int d0 = 0; d0 < 8; ++d0) { const char* a = kb[d0 & 3] + (d0 >> 2) * 128;
;         bf16x8 b0 = *reinterpret_cast<const bf16x8*>(a);
;         bf16x8 b1 = *reinterpret_cast<const bf16x8*>(a + 32 * 256);
;         p0 = __builtin_amdgcn_mfma_f32_32x32x16_bf16(b0, qr[d0], p0, 0, 0, 0);
;         p1 = __builtin_amdgcn_mfma_f32_32x32x16_bf16(b1, qr[d0], p1, 0, 0, 0); }
; }
.LBB0_537:
	s_add_i32 s2, s76, 0
	v_add_u32_e32 v237, s2, v193
	ds_read_b128 v[80:83], v217 offset:256
	ds_read_b128 v[84:87], v217 offset:288
	ds_read_b128 v[64:67], v217 offset:384
	ds_read_b128 v[68:71], v217 offset:416
	ds_read_b128 v[88:91], v217 offset:320
	ds_read_b128 v[72:75], v217 offset:448
	ds_read_b128 v[92:95], v217 offset:352
	ds_read_b128 v[76:79], v217 offset:480
	ds_read_b128 v[156:159], v237 offset:49152
	ds_read_b128 v[160:163], v237 offset:57344
	v_add_u32_e32 v238, s2, v194
	v_add_u32_e32 v239, s2, v195
	s_waitcnt lgkmcnt(0)
	v_mfma_f32_32x32x16_bf16 v[80:95], v[156:159], v[96:99], v[80:95]
	v_add_u32_e32 v240, s2, v196
	v_exp_f32_e32 v167, v167
	v_exp_f32_e32 v168, v168
	v_exp_f32_e32 v169, v169
	v_exp_f32_e32 v170, v170
	v_exp_f32_e32 v171, v171
	v_exp_f32_e32 v172, v172
	v_mfma_f32_32x32x16_bf16 v[64:79], v[160:163], v[96:99], v[64:79]
	ds_read_b128 v[156:159], v238 offset:49152
	ds_read_b128 v[160:163], v238 offset:57344
	v_exp_f32_e32 v173, v173
	v_exp_f32_e32 v174, v174
	v_exp_f32_e32 v175, v175
	v_exp_f32_e32 v176, v176
	v_exp_f32_e32 v234, v234
	v_exp_f32_e32 v235, v235
	s_waitcnt lgkmcnt(0)
	v_mfma_f32_32x32x16_bf16 v[80:95], v[156:159], v[100:103], v[80:95]
	v_exp_f32_e32 v236, v236
	v_mfma_f32_32x32x16_bf16 v[64:79], v[160:163], v[100:103], v[64:79]
	ds_read_b128 v[156:159], v239 offset:49152
	ds_read_b128 v[160:163], v239 offset:57344
	s_waitcnt lgkmcnt(0)
	v_mfma_f32_32x32x16_bf16 v[80:95], v[156:159], v[104:107], v[80:95]
	v_mfma_f32_32x32x16_bf16 v[64:79], v[160:163], v[104:107], v[64:79]
	ds_read_b128 v[156:159], v240 offset:49152
	ds_read_b128 v[160:163], v240 offset:57344
	s_waitcnt lgkmcnt(0)
	v_mfma_f32_32x32x16_bf16 v[80:95], v[156:159], v[108:111], v[80:95]
	v_mfma_f32_32x32x16_bf16 v[64:79], v[160:163], v[108:111], v[64:79]
	v_xor_b32_e32 v249, 0x80, v237
	v_xor_b32_e32 v250, 0x80, v238
	v_xor_b32_e32 v251, 0x80, v239
	v_xor_b32_e32 v252, 0x80, v240
	ds_read_b128 v[156:159], v249 offset:49152
	ds_read_b128 v[160:163], v249 offset:57344
	v_exp_f32_e32 v237, v164
	s_waitcnt lgkmcnt(0)
	v_mfma_f32_32x32x16_bf16 v[80:95], v[156:159], v[112:115], v[80:95]
	v_mfma_f32_32x32x16_bf16 v[64:79], v[160:163], v[112:115], v[64:79]
	ds_read_b128 v[156:159], v250 offset:49152
	ds_read_b128 v[160:163], v250 offset:57344
	v_exp_f32_e32 v238, v165
	s_waitcnt lgkmcnt(0)
	v_mfma_f32_32x32x16_bf16 v[80:95], v[156:159], v[116:119], v[80:95]
	v_mfma_f32_32x32x16_bf16 v[64:79], v[160:163], v[116:119], v[64:79]
	ds_read_b128 v[156:159], v251 offset:49152
	ds_read_b128 v[160:163], v251 offset:57344
	v_exp_f32_e32 v239, v166
	s_waitcnt lgkmcnt(0)
	v_mfma_f32_32x32x16_bf16 v[80:95], v[156:159], v[120:123], v[80:95]
	v_mfma_f32_32x32x16_bf16 v[64:79], v[160:163], v[120:123], v[64:79]
	ds_read_b128 v[156:159], v252 offset:49152
	ds_read_b128 v[160:163], v252 offset:57344
	s_waitcnt lgkmcnt(0)
	v_mfma_f32_32x32x16_bf16 v[80:95], v[156:159], v[124:127], v[80:95]
	v_add_f32_e32 v156, 0, v177
	v_add_f32_e32 v156, v178, v156
	v_add_f32_e32 v156, v179, v156
	v_add_f32_e32 v156, v221, v156
	v_add_f32_e32 v156, v222, v156
	v_add_f32_e32 v156, v223, v156
	v_add_f32_e32 v156, v224, v156
	v_add_f32_e32 v156, v225, v156
	v_add_f32_e32 v156, v226, v156
	v_add_f32_e32 v156, v227, v156
	v_add_f32_e32 v156, v228, v156
	v_add_f32_e32 v156, v229, v156
	v_add_f32_e32 v156, v230, v156
	v_add_f32_e32 v156, v231, v156
	v_add_f32_e32 v156, v232, v156
	v_add_f32_e32 v156, v233, v156
	v_add_f32_e32 v156, v237, v156
	v_add_f32_e32 v156, v238, v156
	v_add_f32_e32 v156, v239, v156
	v_add_f32_e32 v156, v167, v156
	v_add_f32_e32 v156, v168, v156
	v_add_f32_e32 v156, v169, v156
	v_add_f32_e32 v156, v170, v156
	v_add_f32_e32 v156, v171, v156
	v_add_f32_e32 v156, v172, v156
	v_add_f32_e32 v156, v173, v156
	v_mfma_f32_32x32x16_bf16 v[64:79], v[160:163], v[124:127], v[64:79]
	v_add_f32_e32 v156, v174, v156
	v_add_f32_e32 v156, v175, v156
	v_add_f32_e32 v156, v176, v156
	v_add_f32_e32 v156, v234, v156
	v_add_f32_e32 v156, v235, v156
	v_add_f32_e32 v156, v236, v156
	v_mov_b32_e32 v157, v156
	s_nop 1
	v_permlane32_swap_b32_e32 v156, v157
	v_cvt_pk_bf16_f32 v158, v177, v178
	v_cvt_pk_bf16_f32 v159, v179, v221
	v_cvt_pk_bf16_f32 v160, v222, v223
	v_cvt_pk_bf16_f32 v161, v224, v225
	v_cvt_pk_bf16_f32 v162, v226, v227
	v_cvt_pk_bf16_f32 v163, v228, v229
	v_cvt_pk_bf16_f32 v164, v230, v231
	v_cvt_pk_bf16_f32 v165, v232, v233
	v_cvt_pk_bf16_f32 v166, v237, v238
	v_cvt_pk_bf16_f32 v167, v239, v167
	v_cvt_pk_bf16_f32 v168, v168, v169
	v_cvt_pk_bf16_f32 v169, v170, v171
	v_cvt_pk_bf16_f32 v170, v172, v173
	v_cvt_pk_bf16_f32 v171, v174, v175
	v_cvt_pk_bf16_f32 v172, v176, v234
	v_cvt_pk_bf16_f32 v173, v235, v236
	s_nop 0
	v_permlane32_swap_b32_e32 v158, v160
	v_permlane32_swap_b32_e32 v159, v161
	v_permlane32_swap_b32_e32 v162, v164
	v_permlane32_swap_b32_e32 v163, v165
	v_permlane32_swap_b32_e32 v166, v168
	v_permlane32_swap_b32_e32 v167, v169
	v_permlane32_swap_b32_e32 v170, v172
	v_permlane32_swap_b32_e32 v171, v173
	v_add_u32_e32 v178, s73, v192
	s_cmp_le_i32 s92, s91
	s_cbranch_scc0 .Lband_1
; #define SBAR() __builtin_amdgcn_sched_barrier(0)
; #define PV_RD(d0, kh, X) do { constexpr int b_ = v_rd_off(d0, 2 * (kh), 0); TRRD(X##l0, b_); TRRD(X##h0, b_ + 2048); TRRD(X##l1, b_ + 4096); TRRD(X##h1, b_ + 6144); } while (0)
; #define PV_MM(d0, X, PA, PB) do { \
;         o[d0] = __builtin_amdgcn_mfma_f32_32x32x16_bf16(PA, (bf16x8){X##l0[0], X##l0[1], X##l0[2], X##l0[3], X##h0[0], X##h0[1], X##h0[2], X##h0[3]}, o[d0], 0, 0, 0);   \
;         o[d0] = __builtin_amdgcn_mfma_f32_32x32x16_bf16(PB, (bf16x8){X##l1[0], X##l1[1], X##l1[2], X##l1[3], X##h1[0], X##h1[1], X##h1[2], X##h1[3]}, o[d0], 0, 0, 0); } while (0)
; #define PV_W4() do { asm volatile("s_waitcnt lgkmcnt(4)" ::: "memory"); SBAR(); } while (0)
; #define PV_W0() do { asm volatile("s_waitcnt lgkmcnt(0)" ::: "memory"); SBAR(); } while (0)
; __device__ __forceinline__ void partialSM(f32x16& p0, f32x16& p1, float& m_reg, float& mn, float& alpha) {
;     float pmax = p0[0];
; #pragma unroll
;     for (int r = 1; r < 16; ++r) pmax = fmaxf(pmax, p0[r]);
; #pragma unroll
;     for (int r = 0; r < 16; ++r) pmax = fmaxf(pmax, p1[r]);
;     { auto rr = __builtin_amdgcn_permlane32_swap(__float_as_uint(pmax), __float_as_uint(pmax), false, false);
;       pmax = fmaxf(__uint_as_float(rr[0]), __uint_as_float(rr[1])); }
; __device__ __forceinline__ void pv_tile(f32x16* o, int vb0, bf16x8 pa0, bf16x8 pa1, bf16x8 pa2, bf16x8 pa3) {
;     ...
;     s16x4 al0, al1, ah0, ah1, bl0, bl1, bh0, bh1;
;     PV_RD(0, 0, a);
;     PV_RD(0, 1, b); PV_W4(); PV_MM(0, a, pa0, pa1); SBAR();
;     PV_RD(1, 0, a); PV_W4(); PV_MM(0, b, pa2, pa3); SBAR();
;     PV_RD(1, 1, b); PV_W4(); PV_MM(1, a, pa0, pa1); SBAR();
;     PV_RD(2, 0, a); PV_W4(); PV_MM(1, b, pa2, pa3); SBAR();
;     PV_RD(2, 1, b); PV_W4(); PV_MM(2, a, pa0, pa1); SBAR();
;     PV_RD(3, 0, a); PV_W4(); PV_MM(2, b, pa2, pa3); SBAR();
;     PV_RD(3, 1, b); PV_W4(); PV_MM(3, a, pa0, pa1); SBAR();
;     PV_W0(); PV_MM(3, b, pa2, pa3);
	ds_read_b64_tr_b16 v[174:175], v178 offset:0
	ds_read_b64_tr_b16 v[176:177], v178 offset:0x800
	ds_read_b64_tr_b16 v[222:223], v178 offset:0x1000
	ds_read_b64_tr_b16 v[224:225], v178 offset:0x1800
	ds_read_b64_tr_b16 v[226:227], v178 offset:0x2000
	ds_read_b64_tr_b16 v[228:229], v178 offset:0x2800
	ds_read_b64_tr_b16 v[230:231], v178 offset:0x3000
	ds_read_b64_tr_b16 v[232:233], v178 offset:0x3800
	s_waitcnt lgkmcnt(4)
	s_nop 0
	v_mfma_f32_32x32x16_bf16 v[48:63], v[158:161], v[174:177], v[48:63]
	v_max_f32_e32 v253, v81, v81
	v_max_f32_e32 v254, v80, v80
	v_mfma_f32_32x32x16_bf16 v[48:63], v[162:165], v[222:225], v[48:63]
	v_max_f32_e32 v253, v254, v253
	v_max3_f32 v253, v253, v82, v83
	ds_read_b64_tr_b16 v[174:175], v178 offset:0x200
	ds_read_b64_tr_b16 v[176:177], v178 offset:0xa00
	ds_read_b64_tr_b16 v[222:223], v178 offset:0x1200
	ds_read_b64_tr_b16 v[224:225], v178 offset:0x1a00
	s_waitcnt lgkmcnt(4)
	v_mfma_f32_32x32x16_bf16 v[48:63], v[166:169], v[226:229], v[48:63]
	v_max3_f32 v253, v253, v84, v85
	v_max3_f32 v253, v253, v86, v87
	v_mfma_f32_32x32x16_bf16 v[48:63], v[170:173], v[230:233], v[48:63]
	v_max3_f32 v253, v253, v88, v89
	v_max3_f32 v253, v253, v90, v91
	ds_read_b64_tr_b16 v[226:227], v178 offset:0x2200
	ds_read_b64_tr_b16 v[228:229], v178 offset:0x2a00
	ds_read_b64_tr_b16 v[230:231], v178 offset:0x3200
	ds_read_b64_tr_b16 v[232:233], v178 offset:0x3a00
	s_waitcnt lgkmcnt(4)
	v_mfma_f32_32x32x16_bf16 v[32:47], v[158:161], v[174:177], v[32:47]
	v_max3_f32 v253, v253, v92, v93
	v_max3_f32 v253, v253, v94, v95
	v_mfma_f32_32x32x16_bf16 v[32:47], v[162:165], v[222:225], v[32:47]
	v_max3_f32 v253, v253, v64, v65
	v_max3_f32 v253, v253, v66, v67
	ds_read_b64_tr_b16 v[174:175], v178 offset:0x400
	ds_read_b64_tr_b16 v[176:177], v178 offset:0xc00
	ds_read_b64_tr_b16 v[222:223], v178 offset:0x1400
	ds_read_b64_tr_b16 v[224:225], v178 offset:0x1c00
	s_waitcnt lgkmcnt(4)
	v_mfma_f32_32x32x16_bf16 v[32:47], v[166:169], v[226:229], v[32:47]
	v_max3_f32 v253, v253, v68, v69
	v_max3_f32 v253, v253, v70, v71
	v_mfma_f32_32x32x16_bf16 v[32:47], v[170:173], v[230:233], v[32:47]
	v_max3_f32 v253, v253, v72, v73
	v_max3_f32 v253, v253, v74, v75
	ds_read_b64_tr_b16 v[226:227], v178 offset:0x2400
	ds_read_b64_tr_b16 v[228:229], v178 offset:0x2c00
	ds_read_b64_tr_b16 v[230:231], v178 offset:0x3400
	ds_read_b64_tr_b16 v[232:233], v178 offset:0x3c00
	s_waitcnt lgkmcnt(4)
	v_mfma_f32_32x32x16_bf16 v[16:31], v[158:161], v[174:177], v[16:31]
	v_max3_f32 v253, v253, v76, v77
	v_max3_f32 v253, v253, v78, v79
	v_mfma_f32_32x32x16_bf16 v[16:31], v[162:165], v[222:225], v[16:31]
	v_mov_b32_e32 v254, v253
	s_nop 1
	ds_read_b64_tr_b16 v[174:175], v178 offset:0x600
	ds_read_b64_tr_b16 v[176:177], v178 offset:0xe00
	ds_read_b64_tr_b16 v[222:223], v178 offset:0x1600
	ds_read_b64_tr_b16 v[224:225], v178 offset:0x1e00
	s_waitcnt lgkmcnt(4)
	v_mfma_f32_32x32x16_bf16 v[16:31], v[166:169], v[226:229], v[16:31]
	v_permlane32_swap_b32_e32 v253, v254
	v_max_f32_e32 v254, v254, v254
	v_mfma_f32_32x32x16_bf16 v[16:31], v[170:173], v[230:233], v[16:31]
	v_max_f32_e32 v253, v253, v253
	v_max_f32_e32 v253, v253, v254
	ds_read_b64_tr_b16 v[226:227], v178 offset:0x2600
	ds_read_b64_tr_b16 v[228:229], v178 offset:0x2e00
	ds_read_b64_tr_b16 v[230:231], v178 offset:0x3600
	ds_read_b64_tr_b16 v[232:233], v178 offset:0x3e00
	s_waitcnt lgkmcnt(4)
	v_mfma_f32_32x32x16_bf16 v[0:15], v[158:161], v[174:177], v[0:15]
	v_sub_f32_e32 v254, v253, v154
	v_cmp_ge_f32_e32 vcc, s33, v254
	v_mfma_f32_32x32x16_bf16 v[0:15], v[162:165], v[222:225], v[0:15]
	v_max_f32_e32 v254, v154, v154
	v_max_f32_e32 v254, v254, v253
	s_waitcnt lgkmcnt(0)
	v_mfma_f32_32x32x16_bf16 v[0:15], v[166:169], v[226:229], v[0:15]
	v_sub_f32_e32 v253, v154, v254
	v_exp_f32_e32 v253, v253
	v_mfma_f32_32x32x16_bf16 v[0:15], v[170:173], v[230:233], v[0:15]
	v_mov_b32_e32 v158, v253
	v_mov_b32_e32 v159, v254
	s_branch .Lmaxtail_1

; __device__ __forceinline__ void partialSM(f32x16& p0, f32x16& p1, float& m_reg, float& mn, float& alpha) {
;     ...
;     for (int r = 0; r < 16; ++r) p0[r] = p0[r] - mn;
; #pragma unroll
;     for (int r = 0; r < 16; ++r) p1[r] = p1[r] - mn;
; __device__ __forceinline__ void finishSM(f32x16& p0, f32x16& p1, float alpha, float& l_reg, bf16x8& pa0, bf16x8& pa1, bf16x8& pa2, bf16x8& pa3) {
;     ...
;     l_reg = l_reg * alpha + ps;
.LBB0_543:
	v_cndmask_b32_e64 v154, v159, v154, s[2:3]
	v_pk_add_f32 v[80:81], v[80:81], v[154:155] op_sel_hi:[1,0] neg_lo:[0,1] neg_hi:[0,1]
	v_pk_add_f32 v[82:83], v[82:83], v[154:155] op_sel_hi:[1,0] neg_lo:[0,1] neg_hi:[0,1]
	v_pk_add_f32 v[84:85], v[84:85], v[154:155] op_sel_hi:[1,0] neg_lo:[0,1] neg_hi:[0,1]
	v_pk_add_f32 v[86:87], v[86:87], v[154:155] op_sel_hi:[1,0] neg_lo:[0,1] neg_hi:[0,1]
	v_pk_add_f32 v[88:89], v[88:89], v[154:155] op_sel_hi:[1,0] neg_lo:[0,1] neg_hi:[0,1]
	v_pk_add_f32 v[90:91], v[90:91], v[154:155] op_sel_hi:[1,0] neg_lo:[0,1] neg_hi:[0,1]
	v_pk_add_f32 v[92:93], v[92:93], v[154:155] op_sel_hi:[1,0] neg_lo:[0,1] neg_hi:[0,1]
	v_pk_add_f32 v[94:95], v[94:95], v[154:155] op_sel_hi:[1,0] neg_lo:[0,1] neg_hi:[0,1]
	v_exp_f32_e32 v221, v80
	v_exp_f32_e32 v236, v81
	v_exp_f32_e32 v233, v82
	v_exp_f32_e32 v235, v83
	v_exp_f32_e32 v231, v84
	v_exp_f32_e32 v234, v85
	v_exp_f32_e32 v230, v86
	v_exp_f32_e32 v232, v87
	v_exp_f32_e32 v227, v88
	v_exp_f32_e32 v229, v89
	v_exp_f32_e32 v225, v90
	v_exp_f32_e32 v228, v91
	v_exp_f32_e32 v223, v92
	v_exp_f32_e32 v226, v93
	v_exp_f32_e32 v222, v94
	v_exp_f32_e32 v224, v95
	v_pk_add_f32 v[168:169], v[64:65], v[154:155] op_sel_hi:[1,0] neg_lo:[0,1] neg_hi:[0,1]
	v_add_f32_e32 v64, v218, v219
	v_fmac_f32_e32 v64, v147, v215
	v_add_f32_e32 v215, v156, v157
	v_pk_add_f32 v[172:173], v[66:67], v[154:155] op_sel_hi:[1,0] neg_lo:[0,1] neg_hi:[0,1]
	v_pk_add_f32 v[176:177], v[68:69], v[154:155] op_sel_hi:[1,0] neg_lo:[0,1] neg_hi:[0,1]
	v_pk_add_f32 v[166:167], v[70:71], v[154:155] op_sel_hi:[1,0] neg_lo:[0,1] neg_hi:[0,1]
	v_pk_add_f32 v[170:171], v[72:73], v[154:155] op_sel_hi:[1,0] neg_lo:[0,1] neg_hi:[0,1]
	v_pk_add_f32 v[174:175], v[74:75], v[154:155] op_sel_hi:[1,0] neg_lo:[0,1] neg_hi:[0,1]
	v_pk_add_f32 v[178:179], v[76:77], v[154:155] op_sel_hi:[1,0] neg_lo:[0,1] neg_hi:[0,1]
	v_pk_add_f32 v[164:165], v[78:79], v[154:155] op_sel_hi:[1,0] neg_lo:[0,1] neg_hi:[0,1]
	v_fmac_f32_e32 v215, v64, v220
	v_add_u32_e32 v216, 0xffffff80, v216
	v_add_u32_e32 v217, 0x200, v217
	s_mov_b64 s[2:3], -1
	s_and_b64 vcc, exec, s[86:87]
	s_cbranch_vccz .LBB0_549
	s_and_b64 vcc, exec, s[96:97]
	s_cbranch_vccz .LBB0_546
	s_waitcnt vmcnt(0) lgkmcnt(0)
	s_barrier
	s_mov_b64 s[2:3], 0

; __device__ __forceinline__ void fox_block(const BlockRef& cur, const BlockRef& nxt, char* lds, Seam& S, const int tid) {
;     ...
;     for (int t = 1; t + 1 < NT; t += 2) {
;         STEP(pB0, pB1, mnB, alB, pA0, pA1, alA, t);
;         STEP(pA0, pA1, mnA, alA, pB0, pB1, alB, t + 1);
.LBB0_551:
	s_add_i32 s2, s90, 0x4000
	s_cmpk_lg_u32 s90, 0x8000
	s_cselect_b32 s3, s2, 0
	s_addk_i32 s92, 0x80
	s_add_u32 s68, s68, 0x8000
	s_addc_u32 s69, s69, 0
	s_add_i32 s71, s71, 2
	s_and_b64 vcc, exec, s[86:87]
	s_cbranch_vccnz .LBB0_553
	s_mov_b32 s2, s76
	s_mov_b32 s73, s72
	s_mov_b32 s76, s90
	s_mov_b32 s72, s3
	v_mov_b32_e32 v147, v158
	s_branch .LBB0_521

; #define LAS __attribute__((address_space(3)))
; __device__ __forceinline__ void finishSM(f32x16& p0, f32x16& p1, float alpha, float& l_reg, bf16x8& pa0, bf16x8& pa1, bf16x8& pa2, bf16x8& pa3) {
; #pragma unroll
;     for (int r = 0; r < 16; ++r) p1[r] = __builtin_amdgcn_exp2f(p1[r]);
;     float ps = 0;
; #pragma unroll
;     for (int r = 0; r < 16; ++r) ps += p0[r];
; #pragma unroll
;     for (int r = 0; r < 16; ++r) ps += p1[r];
;     { auto rr = __builtin_amdgcn_permlane32_swap(__float_as_uint(ps), __float_as_uint(ps), false, false);
;       ps = __uint_as_float(rr[0]) + __uint_as_float(rr[1]); }
;     l_reg = l_reg * alpha + ps;
;     ...
;     PK4(p0, 0, pa0); PK4(p0, 8, pa1); PK4(p1, 0, pa2); PK4(p1, 8, pa3);
; __device__ __forceinline__ void qkt(f32x16& p0, f32x16& p1, const char* Kslot, int r32, int hi, const bf16x8* qr, const LAS f32x4* cp) {
; #pragma unroll
;     for (int g = 0; g < 4; ++g) { const f32x4 c0 = cp[2 * g], c1 = cp[8 + 2 * g];
; #pragma unroll
;         for (int j = 0; j < 4; ++j) { p0[4 * g + j] = c0[j]; p1[4 * g + j] = c1[j]; } }
;     const char* kb[4];
; #pragma unroll
;     for (int dd = 0; dd < 4; ++dd) kb[dd] = Kslot + KSWZ(r32, (dd * 16 + hi * 8) * 2);
; #pragma unroll
;     for (int d0 = 0; d0 < 8; ++d0) { const char* a = kb[d0 & 3] + (d0 >> 2) * 128;
;         bf16x8 b0 = *reinterpret_cast<const bf16x8*>(a);
;         bf16x8 b1 = *reinterpret_cast<const bf16x8*>(a + 32 * 256);
;         p0 = __builtin_amdgcn_mfma_f32_32x32x16_bf16(b0, qr[d0], p0, 0, 0, 0);
;         p1 = __builtin_amdgcn_mfma_f32_32x32x16_bf16(b1, qr[d0], p1, 0, 0, 0); }
; }
.LBB0_556:
	s_add_i32 s3, s73, 0
	v_add_u32_e32 v175, s3, v193
	ds_read_b128 v[80:83], v197
	ds_read_b128 v[84:87], v197 offset:32
	ds_read_b128 v[64:67], v197 offset:128
	ds_read_b128 v[68:71], v197 offset:160
	ds_read_b128 v[88:91], v197 offset:64
	ds_read_b128 v[72:75], v197 offset:192
	ds_read_b128 v[92:95], v197 offset:96
	ds_read_b128 v[76:79], v197 offset:224
	ds_read_b128 v[212:215], v175 offset:49152
	ds_read_b128 v[216:219], v175 offset:57344
	s_add_i32 s3, s87, -1
	s_cmp_lt_u32 s3, s89
	s_cselect_b64 s[78:79], -1, 0
	s_cmp_ge_u32 s3, s89
	s_cselect_b64 s[66:67], -1, 0
	s_and_b64 vcc, exec, s[66:67]
	v_lshl_add_u64 v[146:147], s[82:83], 0, v[128:129]
	v_lshl_add_u64 v[148:149], s[82:83], 0, v[138:139]
	s_cbranch_vccnz .LBB0_558
	s_add_i32 s3, s86, s72
	v_lshl_add_u64 v[250:251], v[146:147], 0, s[80:81]
	s_add_i32 m0, s3, 0xc000
	s_add_i32 s3, s3, 0xc400
	v_lshl_add_u64 v[252:253], v[148:149], 0, s[80:81]
	global_load_lds_dwordx4 v[250:251], off
	s_mov_b32 m0, s3
	s_nop 0
	global_load_lds_dwordx4 v[252:253], off
.LBB0_558:
	s_add_i32 s3, s86, s90
	v_lshl_add_u64 v[150:151], s[82:83], 0, v[140:141]
	v_lshl_add_u64 v[250:251], v[150:151], 0, s[84:85]
	s_mov_b32 m0, s3
	v_lshl_add_u64 v[152:153], s[82:83], 0, v[142:143]
	global_load_lds_dwordx4 v[250:251], off
	v_lshl_add_u64 v[250:251], v[152:153], 0, s[84:85]
	s_add_i32 m0, s3, 0x400
	s_nop 0
	global_load_lds_dwordx4 v[250:251], off
	s_add_i32 s3, s73, 0
	v_add_u32_e32 v176, s3, v194
	v_add_u32_e32 v177, s3, v195
	s_waitcnt lgkmcnt(0)
	v_mfma_f32_32x32x16_bf16 v[80:95], v[212:215], v[96:99], v[80:95]
	v_add_u32_e32 v220, s3, v196
	v_exp_f32_e32 v163, v163
	v_exp_f32_e32 v166, v166
	v_exp_f32_e32 v167, v167
	v_exp_f32_e32 v168, v168
	v_exp_f32_e32 v169, v169
	v_exp_f32_e32 v221, v155
	v_mfma_f32_32x32x16_bf16 v[64:79], v[216:219], v[96:99], v[64:79]
	ds_read_b128 v[212:215], v176 offset:49152
	ds_read_b128 v[216:219], v176 offset:57344
	s_waitcnt lgkmcnt(0)
	v_mfma_f32_32x32x16_bf16 v[80:95], v[212:215], v[100:103], v[80:95]
	v_mfma_f32_32x32x16_bf16 v[64:79], v[216:219], v[100:103], v[64:79]
	ds_read_b128 v[212:215], v177 offset:49152
	ds_read_b128 v[216:219], v177 offset:57344
	s_waitcnt lgkmcnt(0)
	v_mfma_f32_32x32x16_bf16 v[80:95], v[212:215], v[104:107], v[80:95]
	v_mfma_f32_32x32x16_bf16 v[64:79], v[216:219], v[104:107], v[64:79]
	ds_read_b128 v[212:215], v220 offset:49152
	ds_read_b128 v[216:219], v220 offset:57344
	s_waitcnt lgkmcnt(0)
	v_mfma_f32_32x32x16_bf16 v[80:95], v[212:215], v[108:111], v[80:95]
	v_mfma_f32_32x32x16_bf16 v[64:79], v[216:219], v[108:111], v[64:79]
	v_xor_b32_e32 v249, 0x80, v175
	v_xor_b32_e32 v250, 0x80, v176
	v_xor_b32_e32 v251, 0x80, v177
	v_xor_b32_e32 v252, 0x80, v220
	ds_read_b128 v[212:215], v249 offset:49152
	ds_read_b128 v[216:219], v249 offset:57344
	s_waitcnt lgkmcnt(0)
	v_mfma_f32_32x32x16_bf16 v[80:95], v[212:215], v[112:115], v[80:95]
	v_mfma_f32_32x32x16_bf16 v[64:79], v[216:219], v[112:115], v[64:79]
	ds_read_b128 v[212:215], v250 offset:49152
	ds_read_b128 v[216:219], v250 offset:57344
	s_waitcnt lgkmcnt(0)
	v_mfma_f32_32x32x16_bf16 v[80:95], v[212:215], v[116:119], v[80:95]
	v_mfma_f32_32x32x16_bf16 v[64:79], v[216:219], v[116:119], v[64:79]
	ds_read_b128 v[212:215], v251 offset:49152
	ds_read_b128 v[216:219], v251 offset:57344
	v_exp_f32_e32 v177, v158
	s_waitcnt lgkmcnt(0)
	v_mfma_f32_32x32x16_bf16 v[80:95], v[212:215], v[120:123], v[80:95]
	v_mfma_f32_32x32x16_bf16 v[64:79], v[216:219], v[120:123], v[64:79]
	ds_read_b128 v[212:215], v252 offset:49152
	ds_read_b128 v[216:219], v252 offset:57344
	v_exp_f32_e32 v220, v154
	v_add_f32_e32 v154, 0, v178
	v_add_f32_e32 v154, v211, v154
	v_add_f32_e32 v154, v208, v154
	v_add_f32_e32 v154, v210, v154
	v_add_f32_e32 v154, v206, v154
	v_add_f32_e32 v154, v209, v154
	v_add_f32_e32 v154, v205, v154
	v_add_f32_e32 v154, v207, v154
	v_add_f32_e32 v154, v202, v154
	v_add_f32_e32 v154, v204, v154
	v_add_f32_e32 v154, v200, v154
	v_add_f32_e32 v154, v203, v154
	v_add_f32_e32 v154, v198, v154
	s_waitcnt lgkmcnt(0)
	v_mfma_f32_32x32x16_bf16 v[80:95], v[212:215], v[124:127], v[80:95]
	v_exp_f32_e32 v212, v159
	v_add_f32_e32 v154, v201, v154
	v_exp_f32_e32 v213, v162
	v_add_f32_e32 v154, v179, v154
	v_add_f32_e32 v154, v199, v154
	v_add_f32_e32 v154, v177, v154
	v_add_f32_e32 v154, v212, v154
	v_exp_f32_e32 v214, v156
	v_add_f32_e32 v154, v213, v154
	v_exp_f32_e32 v215, v157
	v_add_f32_e32 v154, v163, v154
	v_mfma_f32_32x32x16_bf16 v[64:79], v[216:219], v[124:127], v[64:79]
	v_exp_f32_e32 v216, v160
	v_add_f32_e32 v154, v166, v154
	v_exp_f32_e32 v217, v161
	v_add_f32_e32 v154, v167, v154
	v_exp_f32_e32 v218, v164
	v_add_f32_e32 v154, v214, v154
	v_exp_f32_e32 v219, v165
	v_add_f32_e32 v154, v215, v154
	v_add_f32_e32 v154, v216, v154
	v_add_f32_e32 v154, v217, v154
	v_add_f32_e32 v154, v218, v154
	v_add_f32_e32 v154, v219, v154
	v_add_f32_e32 v154, v168, v154
	v_add_f32_e32 v154, v169, v154
	v_add_f32_e32 v154, v220, v154
	v_add_f32_e32 v175, v221, v154
	v_mov_b32_e32 v176, v175
	s_nop 1
	v_permlane32_swap_b32_e32 v175, v176
	v_cvt_pk_bf16_f32 v154, v178, v211
	v_cvt_pk_bf16_f32 v155, v208, v210
	v_cvt_pk_bf16_f32 v156, v206, v209
	v_cvt_pk_bf16_f32 v157, v205, v207
	v_cvt_pk_bf16_f32 v158, v202, v204
	v_cvt_pk_bf16_f32 v159, v200, v203
	v_cvt_pk_bf16_f32 v160, v198, v201
	v_cvt_pk_bf16_f32 v161, v179, v199
	v_cvt_pk_bf16_f32 v162, v177, v212
	v_cvt_pk_bf16_f32 v163, v213, v163
	v_cvt_pk_bf16_f32 v164, v166, v167
	v_cvt_pk_bf16_f32 v165, v214, v215
	v_cvt_pk_bf16_f32 v166, v216, v217
	v_cvt_pk_bf16_f32 v167, v218, v219
	v_cvt_pk_bf16_f32 v168, v168, v169
	v_cvt_pk_bf16_f32 v169, v220, v221
	s_nop 0
	v_permlane32_swap_b32_e32 v154, v156
	v_permlane32_swap_b32_e32 v155, v157
	v_permlane32_swap_b32_e32 v158, v160
	v_permlane32_swap_b32_e32 v159, v161
	v_permlane32_swap_b32_e32 v162, v164
	v_permlane32_swap_b32_e32 v163, v165
	v_permlane32_swap_b32_e32 v166, v168
	v_permlane32_swap_b32_e32 v167, v169
	v_add_u32_e32 v177, s2, v192
	s_sub_i32 s2, s91, 64
	s_cmp_le_i32 s2, s88
	s_cbranch_scc0 .Lband_2
; #define SBAR() __builtin_amdgcn_sched_barrier(0)
; #define PV_RD(d0, kh, X) do { constexpr int b_ = v_rd_off(d0, 2 * (kh), 0); TRRD(X##l0, b_); TRRD(X##h0, b_ + 2048); TRRD(X##l1, b_ + 4096); TRRD(X##h1, b_ + 6144); } while (0)
; #define PV_MM(d0, X, PA, PB) do { \
;         o[d0] = __builtin_amdgcn_mfma_f32_32x32x16_bf16(PA, (bf16x8){X##l0[0], X##l0[1], X##l0[2], X##l0[3], X##h0[0], X##h0[1], X##h0[2], X##h0[3]}, o[d0], 0, 0, 0);   \
;         o[d0] = __builtin_amdgcn_mfma_f32_32x32x16_bf16(PB, (bf16x8){X##l1[0], X##l1[1], X##l1[2], X##l1[3], X##h1[0], X##h1[1], X##h1[2], X##h1[3]}, o[d0], 0, 0, 0); } while (0)
; #define PV_W4() do { asm volatile("s_waitcnt lgkmcnt(4)" ::: "memory"); SBAR(); } while (0)
; #define PV_W0() do { asm volatile("s_waitcnt lgkmcnt(0)" ::: "memory"); SBAR(); } while (0)
; __device__ __forceinline__ void partialSM(f32x16& p0, f32x16& p1, float& m_reg, float& mn, float& alpha) {
;     float pmax = p0[0];
; #pragma unroll
;     for (int r = 1; r < 16; ++r) pmax = fmaxf(pmax, p0[r]);
; #pragma unroll
;     for (int r = 0; r < 16; ++r) pmax = fmaxf(pmax, p1[r]);
;     { auto rr = __builtin_amdgcn_permlane32_swap(__float_as_uint(pmax), __float_as_uint(pmax), false, false);
;       pmax = fmaxf(__uint_as_float(rr[0]), __uint_as_float(rr[1])); }
; __device__ __forceinline__ void pv_tile(f32x16* o, int vb0, bf16x8 pa0, bf16x8 pa1, bf16x8 pa2, bf16x8 pa3) {
;     ...
;     s16x4 al0, al1, ah0, ah1, bl0, bl1, bh0, bh1;
;     PV_RD(0, 0, a);
;     PV_RD(0, 1, b); PV_W4(); PV_MM(0, a, pa0, pa1); SBAR();
;     PV_RD(1, 0, a); PV_W4(); PV_MM(0, b, pa2, pa3); SBAR();
;     PV_RD(1, 1, b); PV_W4(); PV_MM(1, a, pa0, pa1); SBAR();
;     PV_RD(2, 0, a); PV_W4(); PV_MM(1, b, pa2, pa3); SBAR();
;     PV_RD(2, 1, b); PV_W4(); PV_MM(2, a, pa0, pa1); SBAR();
;     PV_RD(3, 0, a); PV_W4(); PV_MM(2, b, pa2, pa3); SBAR();
;     PV_RD(3, 1, b); PV_W4(); PV_MM(3, a, pa0, pa1); SBAR();
;     PV_W0(); PV_MM(3, b, pa2, pa3);
	ds_read_b64_tr_b16 v[198:199], v177 offset:0
	ds_read_b64_tr_b16 v[200:201], v177 offset:0x800
	ds_read_b64_tr_b16 v[202:203], v177 offset:0x1000
	ds_read_b64_tr_b16 v[204:205], v177 offset:0x1800
	ds_read_b64_tr_b16 v[206:207], v177 offset:0x2000
	ds_read_b64_tr_b16 v[208:209], v177 offset:0x2800
	ds_read_b64_tr_b16 v[210:211], v177 offset:0x3000
	ds_read_b64_tr_b16 v[212:213], v177 offset:0x3800
	s_waitcnt lgkmcnt(4)
	s_nop 0
	v_mfma_f32_32x32x16_bf16 v[48:63], v[154:157], v[198:201], v[48:63]
	v_max_f32_e32 v253, v81, v81
	v_max_f32_e32 v254, v80, v80
	v_mfma_f32_32x32x16_bf16 v[48:63], v[158:161], v[202:205], v[48:63]
	v_max_f32_e32 v253, v254, v253
	v_max3_f32 v253, v253, v82, v83
	ds_read_b64_tr_b16 v[198:199], v177 offset:0x200
	ds_read_b64_tr_b16 v[200:201], v177 offset:0xa00
	ds_read_b64_tr_b16 v[202:203], v177 offset:0x1200
	ds_read_b64_tr_b16 v[204:205], v177 offset:0x1a00
	s_waitcnt lgkmcnt(4)
	v_mfma_f32_32x32x16_bf16 v[48:63], v[162:165], v[206:209], v[48:63]
	v_max3_f32 v253, v253, v84, v85
	v_max3_f32 v253, v253, v86, v87
	v_mfma_f32_32x32x16_bf16 v[48:63], v[166:169], v[210:213], v[48:63]
	v_max3_f32 v253, v253, v88, v89
	v_max3_f32 v253, v253, v90, v91
	ds_read_b64_tr_b16 v[206:207], v177 offset:0x2200
	ds_read_b64_tr_b16 v[208:209], v177 offset:0x2a00
	ds_read_b64_tr_b16 v[210:211], v177 offset:0x3200
	ds_read_b64_tr_b16 v[212:213], v177 offset:0x3a00
	s_waitcnt lgkmcnt(4)
	v_mfma_f32_32x32x16_bf16 v[32:47], v[154:157], v[198:201], v[32:47]
	v_max3_f32 v253, v253, v92, v93
	v_max3_f32 v253, v253, v94, v95
	v_mfma_f32_32x32x16_bf16 v[32:47], v[158:161], v[202:205], v[32:47]
	v_max3_f32 v253, v253, v64, v65
	v_max3_f32 v253, v253, v66, v67
	ds_read_b64_tr_b16 v[198:199], v177 offset:0x400
	ds_read_b64_tr_b16 v[200:201], v177 offset:0xc00
	ds_read_b64_tr_b16 v[202:203], v177 offset:0x1400
	ds_read_b64_tr_b16 v[204:205], v177 offset:0x1c00
	s_waitcnt lgkmcnt(4)
	v_mfma_f32_32x32x16_bf16 v[32:47], v[162:165], v[206:209], v[32:47]
	v_max3_f32 v253, v253, v68, v69
	v_max3_f32 v253, v253, v70, v71
	v_mfma_f32_32x32x16_bf16 v[32:47], v[166:169], v[210:213], v[32:47]
	v_max3_f32 v253, v253, v72, v73
	v_max3_f32 v253, v253, v74, v75
	ds_read_b64_tr_b16 v[206:207], v177 offset:0x2400
	ds_read_b64_tr_b16 v[208:209], v177 offset:0x2c00
	ds_read_b64_tr_b16 v[210:211], v177 offset:0x3400
	ds_read_b64_tr_b16 v[212:213], v177 offset:0x3c00
	s_waitcnt lgkmcnt(4)
	v_mfma_f32_32x32x16_bf16 v[16:31], v[154:157], v[198:201], v[16:31]
	v_max3_f32 v253, v253, v76, v77
	v_max3_f32 v253, v253, v78, v79
	v_mfma_f32_32x32x16_bf16 v[16:31], v[158:161], v[202:205], v[16:31]
	v_mov_b32_e32 v254, v253
	s_nop 1
	ds_read_b64_tr_b16 v[198:199], v177 offset:0x600
	ds_read_b64_tr_b16 v[200:201], v177 offset:0xe00
	ds_read_b64_tr_b16 v[202:203], v177 offset:0x1600
	ds_read_b64_tr_b16 v[204:205], v177 offset:0x1e00
	s_waitcnt lgkmcnt(4)
	v_mfma_f32_32x32x16_bf16 v[16:31], v[162:165], v[206:209], v[16:31]
	v_permlane32_swap_b32_e32 v253, v254
	v_max_f32_e32 v254, v254, v254
	v_mfma_f32_32x32x16_bf16 v[16:31], v[166:169], v[210:213], v[16:31]
	v_max_f32_e32 v253, v253, v253
	v_max_f32_e32 v253, v253, v254
	ds_read_b64_tr_b16 v[206:207], v177 offset:0x2600
	ds_read_b64_tr_b16 v[208:209], v177 offset:0x2e00
	ds_read_b64_tr_b16 v[210:211], v177 offset:0x3600
	ds_read_b64_tr_b16 v[212:213], v177 offset:0x3e00
	s_waitcnt lgkmcnt(4)
	v_mfma_f32_32x32x16_bf16 v[0:15], v[154:157], v[198:201], v[0:15]
	v_sub_f32_e32 v254, v253, v144
	v_cmp_ge_f32_e32 vcc, s33, v254
	v_mfma_f32_32x32x16_bf16 v[0:15], v[158:161], v[202:205], v[0:15]
	v_max_f32_e32 v254, v144, v144
	v_max_f32_e32 v253, v254, v253
	s_waitcnt lgkmcnt(0)
	v_mfma_f32_32x32x16_bf16 v[0:15], v[162:165], v[206:209], v[0:15]
	v_sub_f32_e32 v254, v144, v253
	v_exp_f32_e32 v254, v254
	v_mfma_f32_32x32x16_bf16 v[0:15], v[166:169], v[210:213], v[0:15]
	v_mov_b32_e32 v154, v253
	v_mov_b32_e32 v155, v254
	s_branch .Lmaxtail_2

; __device__ __forceinline__ void partialSM(f32x16& p0, f32x16& p1, float& m_reg, float& mn, float& alpha) {
;     ...
;     if (__builtin_expect(__all((pmax - m_reg) <= THR2), 1)) { mn = m_reg; alpha = 1.f; }
;     else { mn = fmaxf(m_reg, pmax); alpha = __builtin_amdgcn_exp2f(m_reg - mn); m_reg = mn; }
; #pragma unroll
;     for (int r = 0; r < 16; ++r) p0[r] = p0[r] - mn;
; #pragma unroll
;     for (int r = 0; r < 16; ++r) p1[r] = p1[r] - mn;
; #pragma unroll
;     for (int r = 0; r < 16; ++r) p0[r] = __builtin_amdgcn_exp2f(p0[r]);
; }
.LBB0_564:
	v_cndmask_b32_e64 v144, v154, v144, s[2:3]
	v_pk_add_f32 v[80:81], v[80:81], v[144:145] op_sel_hi:[1,0] neg_lo:[0,1] neg_hi:[0,1]
	v_pk_add_f32 v[82:83], v[82:83], v[144:145] op_sel_hi:[1,0] neg_lo:[0,1] neg_hi:[0,1]
	v_pk_add_f32 v[84:85], v[84:85], v[144:145] op_sel_hi:[1,0] neg_lo:[0,1] neg_hi:[0,1]
	v_pk_add_f32 v[86:87], v[86:87], v[144:145] op_sel_hi:[1,0] neg_lo:[0,1] neg_hi:[0,1]
	v_pk_add_f32 v[88:89], v[88:89], v[144:145] op_sel_hi:[1,0] neg_lo:[0,1] neg_hi:[0,1]
	v_pk_add_f32 v[90:91], v[90:91], v[144:145] op_sel_hi:[1,0] neg_lo:[0,1] neg_hi:[0,1]
	v_pk_add_f32 v[92:93], v[92:93], v[144:145] op_sel_hi:[1,0] neg_lo:[0,1] neg_hi:[0,1]
	v_pk_add_f32 v[94:95], v[94:95], v[144:145] op_sel_hi:[1,0] neg_lo:[0,1] neg_hi:[0,1]
	v_pk_add_f32 v[154:155], v[64:65], v[144:145] op_sel_hi:[1,0] neg_lo:[0,1] neg_hi:[0,1]
	v_pk_add_f32 v[156:157], v[66:67], v[144:145] op_sel_hi:[1,0] neg_lo:[0,1] neg_hi:[0,1]
	v_pk_add_f32 v[158:159], v[68:69], v[144:145] op_sel_hi:[1,0] neg_lo:[0,1] neg_hi:[0,1]
	v_pk_add_f32 v[160:161], v[70:71], v[144:145] op_sel_hi:[1,0] neg_lo:[0,1] neg_hi:[0,1]
	v_pk_add_f32 v[162:163], v[72:73], v[144:145] op_sel_hi:[1,0] neg_lo:[0,1] neg_hi:[0,1]
	v_pk_add_f32 v[164:165], v[74:75], v[144:145] op_sel_hi:[1,0] neg_lo:[0,1] neg_hi:[0,1]
	v_sub_f32_e32 v166, v76, v144
	v_exp_f32_e32 v167, v80
	v_exp_f32_e32 v168, v81
	v_exp_f32_e32 v169, v82
	v_exp_f32_e32 v178, v83
	v_exp_f32_e32 v179, v84
	v_exp_f32_e32 v198, v85
	v_exp_f32_e32 v199, v86
	v_exp_f32_e32 v200, v87
	v_exp_f32_e32 v201, v88
	v_exp_f32_e32 v202, v89
	v_exp_f32_e32 v203, v90
	v_exp_f32_e32 v204, v91
	v_exp_f32_e32 v205, v92
	v_exp_f32_e32 v206, v93
	v_exp_f32_e32 v207, v94
	v_exp_f32_e32 v208, v95
	v_sub_f32_e32 v209, v77, v144
	v_pk_add_f32 v[210:211], v[78:79], v[144:145] op_sel_hi:[1,0] neg_lo:[0,1] neg_hi:[0,1]
	s_mov_b64 s[4:5], -1
	s_and_b64 vcc, exec, s[66:67]
	s_cbranch_vccz .LBB0_566
	s_waitcnt vmcnt(2) lgkmcnt(0)
	s_barrier
	s_mov_b64 s[4:5], 0

; #define LAS __attribute__((address_space(3)))
; __device__ __forceinline__ void finishSM(f32x16& p0, f32x16& p1, float alpha, float& l_reg, bf16x8& pa0, bf16x8& pa1, bf16x8& pa2, bf16x8& pa3) {
; #pragma unroll
;     for (int r = 0; r < 16; ++r) p1[r] = __builtin_amdgcn_exp2f(p1[r]);
;     float ps = 0;
; #pragma unroll
;     for (int r = 0; r < 16; ++r) ps += p0[r];
; #pragma unroll
;     for (int r = 0; r < 16; ++r) ps += p1[r];
;     { auto rr = __builtin_amdgcn_permlane32_swap(__float_as_uint(ps), __float_as_uint(ps), false, false);
;       ps = __uint_as_float(rr[0]) + __uint_as_float(rr[1]); }
;     l_reg = l_reg * alpha + ps;
;     ...
;     PK4(p0, 0, pa0); PK4(p0, 8, pa1); PK4(p1, 0, pa2); PK4(p1, 8, pa3);
; __device__ __forceinline__ void qkt(f32x16& p0, f32x16& p1, const char* Kslot, int r32, int hi, const bf16x8* qr, const LAS f32x4* cp) {
; #pragma unroll
;     for (int g = 0; g < 4; ++g) { const f32x4 c0 = cp[2 * g], c1 = cp[8 + 2 * g];
; #pragma unroll
;         for (int j = 0; j < 4; ++j) { p0[4 * g + j] = c0[j]; p1[4 * g + j] = c1[j]; } }
;     const char* kb[4];
; #pragma unroll
;     for (int dd = 0; dd < 4; ++dd) kb[dd] = Kslot + KSWZ(r32, (dd * 16 + hi * 8) * 2);
; #pragma unroll
;     for (int d0 = 0; d0 < 8; ++d0) { const char* a = kb[d0 & 3] + (d0 >> 2) * 128;
;         bf16x8 b0 = *reinterpret_cast<const bf16x8*>(a);
;         bf16x8 b1 = *reinterpret_cast<const bf16x8*>(a + 32 * 256);
;         p0 = __builtin_amdgcn_mfma_f32_32x32x16_bf16(b0, qr[d0], p0, 0, 0, 0);
;         p1 = __builtin_amdgcn_mfma_f32_32x32x16_bf16(b1, qr[d0], p1, 0, 0, 0); }
; }
.LBB0_572:
	s_add_i32 s2, s90, 0
	v_add_u32_e32 v212, s2, v193
	ds_read_b128 v[80:83], v197 offset:256
	ds_read_b128 v[84:87], v197 offset:288
	ds_read_b128 v[64:67], v197 offset:384
	ds_read_b128 v[68:71], v197 offset:416
	ds_read_b128 v[88:91], v197 offset:320
	ds_read_b128 v[72:75], v197 offset:448
	ds_read_b128 v[92:95], v197 offset:352
	ds_read_b128 v[76:79], v197 offset:480
	ds_read_b128 v[146:149], v212 offset:49152
	ds_read_b128 v[150:153], v212 offset:57344
	v_add_u32_e32 v213, s2, v194
	v_add_u32_e32 v214, s2, v195
	s_waitcnt lgkmcnt(0)
	v_mfma_f32_32x32x16_bf16 v[80:95], v[146:149], v[96:99], v[80:95]
	v_add_u32_e32 v215, s2, v196
	v_exp_f32_e32 v157, v157
	v_exp_f32_e32 v158, v158
	v_exp_f32_e32 v159, v159
	v_exp_f32_e32 v160, v160
	v_exp_f32_e32 v161, v161
	v_exp_f32_e32 v162, v162
	v_mfma_f32_32x32x16_bf16 v[64:79], v[150:153], v[96:99], v[64:79]
	ds_read_b128 v[146:149], v213 offset:49152
	ds_read_b128 v[150:153], v213 offset:57344
	v_exp_f32_e32 v163, v163
	v_exp_f32_e32 v164, v164
	v_exp_f32_e32 v165, v165
	v_exp_f32_e32 v166, v166
	v_exp_f32_e32 v209, v209
	v_exp_f32_e32 v210, v210
	s_waitcnt lgkmcnt(0)
	v_mfma_f32_32x32x16_bf16 v[80:95], v[146:149], v[100:103], v[80:95]
	v_exp_f32_e32 v211, v211
	v_mfma_f32_32x32x16_bf16 v[64:79], v[150:153], v[100:103], v[64:79]
	ds_read_b128 v[146:149], v214 offset:49152
	ds_read_b128 v[150:153], v214 offset:57344
	s_waitcnt lgkmcnt(0)
	v_mfma_f32_32x32x16_bf16 v[80:95], v[146:149], v[104:107], v[80:95]
	v_mfma_f32_32x32x16_bf16 v[64:79], v[150:153], v[104:107], v[64:79]
	ds_read_b128 v[146:149], v215 offset:49152
	ds_read_b128 v[150:153], v215 offset:57344
	s_waitcnt lgkmcnt(0)
	v_mfma_f32_32x32x16_bf16 v[80:95], v[146:149], v[108:111], v[80:95]
	v_mfma_f32_32x32x16_bf16 v[64:79], v[150:153], v[108:111], v[64:79]
	v_xor_b32_e32 v249, 0x80, v212
	v_xor_b32_e32 v250, 0x80, v213
	v_xor_b32_e32 v251, 0x80, v214
	v_xor_b32_e32 v252, 0x80, v215
	ds_read_b128 v[146:149], v249 offset:49152
	ds_read_b128 v[150:153], v249 offset:57344
	v_exp_f32_e32 v212, v154
	s_waitcnt lgkmcnt(0)
	v_mfma_f32_32x32x16_bf16 v[80:95], v[146:149], v[112:115], v[80:95]
	v_mfma_f32_32x32x16_bf16 v[64:79], v[150:153], v[112:115], v[64:79]
	ds_read_b128 v[146:149], v250 offset:49152
	ds_read_b128 v[150:153], v250 offset:57344
	v_exp_f32_e32 v213, v155
	s_waitcnt lgkmcnt(0)
	v_mfma_f32_32x32x16_bf16 v[80:95], v[146:149], v[116:119], v[80:95]
	v_mfma_f32_32x32x16_bf16 v[64:79], v[150:153], v[116:119], v[64:79]
	ds_read_b128 v[146:149], v251 offset:49152
	ds_read_b128 v[150:153], v251 offset:57344
	v_exp_f32_e32 v214, v156
	s_waitcnt lgkmcnt(0)
	v_mfma_f32_32x32x16_bf16 v[80:95], v[146:149], v[120:123], v[80:95]
	v_mfma_f32_32x32x16_bf16 v[64:79], v[150:153], v[120:123], v[64:79]
	ds_read_b128 v[146:149], v252 offset:49152
	ds_read_b128 v[150:153], v252 offset:57344
	s_waitcnt lgkmcnt(0)
	v_mfma_f32_32x32x16_bf16 v[80:95], v[146:149], v[124:127], v[80:95]
	v_add_f32_e32 v146, 0, v167
	v_add_f32_e32 v146, v168, v146
	v_add_f32_e32 v146, v169, v146
	v_add_f32_e32 v146, v178, v146
	v_add_f32_e32 v146, v179, v146
	v_add_f32_e32 v146, v198, v146
	v_add_f32_e32 v146, v199, v146
	v_add_f32_e32 v146, v200, v146
	v_add_f32_e32 v146, v201, v146
	v_add_f32_e32 v146, v202, v146
	v_add_f32_e32 v146, v203, v146
	v_add_f32_e32 v146, v204, v146
	v_add_f32_e32 v146, v205, v146
	v_add_f32_e32 v146, v206, v146
	v_add_f32_e32 v146, v207, v146
	v_add_f32_e32 v146, v208, v146
	v_add_f32_e32 v146, v212, v146
	v_add_f32_e32 v146, v213, v146
	v_add_f32_e32 v146, v214, v146
	v_add_f32_e32 v146, v157, v146
	v_add_f32_e32 v146, v158, v146
	v_add_f32_e32 v146, v159, v146
	v_add_f32_e32 v146, v160, v146
	v_add_f32_e32 v146, v161, v146
	v_add_f32_e32 v146, v162, v146
	v_add_f32_e32 v146, v163, v146
	v_mfma_f32_32x32x16_bf16 v[64:79], v[150:153], v[124:127], v[64:79]
	v_add_f32_e32 v146, v164, v146
	v_add_f32_e32 v146, v165, v146
	v_add_f32_e32 v146, v166, v146
	v_add_f32_e32 v146, v209, v146
	v_add_f32_e32 v146, v210, v146
	v_add_f32_e32 v146, v211, v146
	v_mov_b32_e32 v147, v146
	s_nop 1
	v_permlane32_swap_b32_e32 v146, v147
	v_cvt_pk_bf16_f32 v148, v167, v168
	v_cvt_pk_bf16_f32 v149, v169, v178
	v_cvt_pk_bf16_f32 v150, v179, v198
	v_cvt_pk_bf16_f32 v151, v199, v200
	v_cvt_pk_bf16_f32 v152, v201, v202
	v_cvt_pk_bf16_f32 v153, v203, v204
	v_cvt_pk_bf16_f32 v154, v205, v206
	v_cvt_pk_bf16_f32 v155, v207, v208
	v_cvt_pk_bf16_f32 v156, v212, v213
	v_cvt_pk_bf16_f32 v157, v214, v157
	v_cvt_pk_bf16_f32 v158, v158, v159
	v_cvt_pk_bf16_f32 v159, v160, v161
	v_cvt_pk_bf16_f32 v160, v162, v163
	v_cvt_pk_bf16_f32 v161, v164, v165
	v_cvt_pk_bf16_f32 v162, v166, v209
	v_cvt_pk_bf16_f32 v163, v210, v211
	s_nop 0
	v_permlane32_swap_b32_e32 v148, v150
	v_permlane32_swap_b32_e32 v149, v151
	v_permlane32_swap_b32_e32 v152, v154
	v_permlane32_swap_b32_e32 v153, v155
	v_permlane32_swap_b32_e32 v156, v158
	v_permlane32_swap_b32_e32 v157, v159
	v_permlane32_swap_b32_e32 v160, v162
	v_permlane32_swap_b32_e32 v161, v163
	v_add_u32_e32 v168, s73, v192
	s_cmp_le_i32 s91, s88
	s_cbranch_scc0 .Lband_3
; #define SBAR() __builtin_amdgcn_sched_barrier(0)
; #define PV_RD(d0, kh, X) do { constexpr int b_ = v_rd_off(d0, 2 * (kh), 0); TRRD(X##l0, b_); TRRD(X##h0, b_ + 2048); TRRD(X##l1, b_ + 4096); TRRD(X##h1, b_ + 6144); } while (0)
; #define PV_MM(d0, X, PA, PB) do { \
;         o[d0] = __builtin_amdgcn_mfma_f32_32x32x16_bf16(PA, (bf16x8){X##l0[0], X##l0[1], X##l0[2], X##l0[3], X##h0[0], X##h0[1], X##h0[2], X##h0[3]}, o[d0], 0, 0, 0);   \
;         o[d0] = __builtin_amdgcn_mfma_f32_32x32x16_bf16(PB, (bf16x8){X##l1[0], X##l1[1], X##l1[2], X##l1[3], X##h1[0], X##h1[1], X##h1[2], X##h1[3]}, o[d0], 0, 0, 0); } while (0)
; #define PV_W4() do { asm volatile("s_waitcnt lgkmcnt(4)" ::: "memory"); SBAR(); } while (0)
; #define PV_W0() do { asm volatile("s_waitcnt lgkmcnt(0)" ::: "memory"); SBAR(); } while (0)
; __device__ __forceinline__ void partialSM(f32x16& p0, f32x16& p1, float& m_reg, float& mn, float& alpha) {
;     float pmax = p0[0];
; #pragma unroll
;     for (int r = 1; r < 16; ++r) pmax = fmaxf(pmax, p0[r]);
; #pragma unroll
;     for (int r = 0; r < 16; ++r) pmax = fmaxf(pmax, p1[r]);
;     { auto rr = __builtin_amdgcn_permlane32_swap(__float_as_uint(pmax), __float_as_uint(pmax), false, false);
;       pmax = fmaxf(__uint_as_float(rr[0]), __uint_as_float(rr[1])); }
; __device__ __forceinline__ void pv_tile(f32x16* o, int vb0, bf16x8 pa0, bf16x8 pa1, bf16x8 pa2, bf16x8 pa3) {
;     ...
;     s16x4 al0, al1, ah0, ah1, bl0, bl1, bh0, bh1;
;     PV_RD(0, 0, a);
;     PV_RD(0, 1, b); PV_W4(); PV_MM(0, a, pa0, pa1); SBAR();
;     PV_RD(1, 0, a); PV_W4(); PV_MM(0, b, pa2, pa3); SBAR();
;     PV_RD(1, 1, b); PV_W4(); PV_MM(1, a, pa0, pa1); SBAR();
;     PV_RD(2, 0, a); PV_W4(); PV_MM(1, b, pa2, pa3); SBAR();
;     PV_RD(2, 1, b); PV_W4(); PV_MM(2, a, pa0, pa1); SBAR();
;     PV_RD(3, 0, a); PV_W4(); PV_MM(2, b, pa2, pa3); SBAR();
;     PV_RD(3, 1, b); PV_W4(); PV_MM(3, a, pa0, pa1); SBAR();
;     PV_W0(); PV_MM(3, b, pa2, pa3);
	ds_read_b64_tr_b16 v[164:165], v168 offset:0
	ds_read_b64_tr_b16 v[166:167], v168 offset:0x800
	ds_read_b64_tr_b16 v[198:199], v168 offset:0x1000
	ds_read_b64_tr_b16 v[200:201], v168 offset:0x1800
	ds_read_b64_tr_b16 v[202:203], v168 offset:0x2000
	ds_read_b64_tr_b16 v[204:205], v168 offset:0x2800
	ds_read_b64_tr_b16 v[206:207], v168 offset:0x3000
	ds_read_b64_tr_b16 v[208:209], v168 offset:0x3800
	s_waitcnt lgkmcnt(4)
	s_nop 0
	v_mfma_f32_32x32x16_bf16 v[48:63], v[148:151], v[164:167], v[48:63]
	v_max_f32_e32 v253, v81, v81
	v_max_f32_e32 v254, v80, v80
	v_mfma_f32_32x32x16_bf16 v[48:63], v[152:155], v[198:201], v[48:63]
	v_max_f32_e32 v253, v254, v253
	v_max3_f32 v253, v253, v82, v83
	ds_read_b64_tr_b16 v[164:165], v168 offset:0x200
	ds_read_b64_tr_b16 v[166:167], v168 offset:0xa00
	ds_read_b64_tr_b16 v[198:199], v168 offset:0x1200
	ds_read_b64_tr_b16 v[200:201], v168 offset:0x1a00
	s_waitcnt lgkmcnt(4)
	v_mfma_f32_32x32x16_bf16 v[48:63], v[156:159], v[202:205], v[48:63]
	v_max3_f32 v253, v253, v84, v85
	v_max3_f32 v253, v253, v86, v87
	v_mfma_f32_32x32x16_bf16 v[48:63], v[160:163], v[206:209], v[48:63]
	v_max3_f32 v253, v253, v88, v89
	v_max3_f32 v253, v253, v90, v91
	ds_read_b64_tr_b16 v[202:203], v168 offset:0x2200
	ds_read_b64_tr_b16 v[204:205], v168 offset:0x2a00
	ds_read_b64_tr_b16 v[206:207], v168 offset:0x3200
	ds_read_b64_tr_b16 v[208:209], v168 offset:0x3a00
	s_waitcnt lgkmcnt(4)
	v_mfma_f32_32x32x16_bf16 v[32:47], v[148:151], v[164:167], v[32:47]
	v_max3_f32 v253, v253, v92, v93
	v_max3_f32 v253, v253, v94, v95
	v_mfma_f32_32x32x16_bf16 v[32:47], v[152:155], v[198:201], v[32:47]
	v_max3_f32 v253, v253, v64, v65
	v_max3_f32 v253, v253, v66, v67
	ds_read_b64_tr_b16 v[164:165], v168 offset:0x400
	ds_read_b64_tr_b16 v[166:167], v168 offset:0xc00
	ds_read_b64_tr_b16 v[198:199], v168 offset:0x1400
	ds_read_b64_tr_b16 v[200:201], v168 offset:0x1c00
	s_waitcnt lgkmcnt(4)
	v_mfma_f32_32x32x16_bf16 v[32:47], v[156:159], v[202:205], v[32:47]
	v_max3_f32 v253, v253, v68, v69
	v_max3_f32 v253, v253, v70, v71
	v_mfma_f32_32x32x16_bf16 v[32:47], v[160:163], v[206:209], v[32:47]
	v_max3_f32 v253, v253, v72, v73
	v_max3_f32 v253, v253, v74, v75
	ds_read_b64_tr_b16 v[202:203], v168 offset:0x2400
	ds_read_b64_tr_b16 v[204:205], v168 offset:0x2c00
	ds_read_b64_tr_b16 v[206:207], v168 offset:0x3400
	ds_read_b64_tr_b16 v[208:209], v168 offset:0x3c00
	s_waitcnt lgkmcnt(4)
	v_mfma_f32_32x32x16_bf16 v[16:31], v[148:151], v[164:167], v[16:31]
	v_max3_f32 v253, v253, v76, v77
	v_max3_f32 v253, v253, v78, v79
	v_mfma_f32_32x32x16_bf16 v[16:31], v[152:155], v[198:201], v[16:31]
	v_mov_b32_e32 v254, v253
	s_nop 1
	ds_read_b64_tr_b16 v[164:165], v168 offset:0x600
	ds_read_b64_tr_b16 v[166:167], v168 offset:0xe00
	ds_read_b64_tr_b16 v[198:199], v168 offset:0x1600
	ds_read_b64_tr_b16 v[200:201], v168 offset:0x1e00
	s_waitcnt lgkmcnt(4)
	v_mfma_f32_32x32x16_bf16 v[16:31], v[156:159], v[202:205], v[16:31]
	v_permlane32_swap_b32_e32 v253, v254
	v_max_f32_e32 v254, v254, v254
	v_mfma_f32_32x32x16_bf16 v[16:31], v[160:163], v[206:209], v[16:31]
	v_max_f32_e32 v253, v253, v253
	v_max_f32_e32 v253, v253, v254
	ds_read_b64_tr_b16 v[202:203], v168 offset:0x2600
	ds_read_b64_tr_b16 v[204:205], v168 offset:0x2e00
	ds_read_b64_tr_b16 v[206:207], v168 offset:0x3600
	ds_read_b64_tr_b16 v[208:209], v168 offset:0x3e00
	s_waitcnt lgkmcnt(4)
	v_mfma_f32_32x32x16_bf16 v[0:15], v[148:151], v[164:167], v[0:15]
	v_sub_f32_e32 v254, v253, v144
	v_cmp_ge_f32_e32 vcc, s33, v254
	v_mfma_f32_32x32x16_bf16 v[0:15], v[152:155], v[198:201], v[0:15]
	v_max_f32_e32 v254, v144, v144
	v_max_f32_e32 v254, v254, v253
	s_waitcnt lgkmcnt(0)
	v_mfma_f32_32x32x16_bf16 v[0:15], v[156:159], v[202:205], v[0:15]
	v_sub_f32_e32 v253, v144, v254
	v_exp_f32_e32 v253, v253
	v_mfma_f32_32x32x16_bf16 v[0:15], v[160:163], v[206:209], v[0:15]
	v_mov_b32_e32 v148, v253
	v_mov_b32_e32 v149, v254
	s_branch .Lmaxtail_3

; __device__ __forceinline__ void partialSM(f32x16& p0, f32x16& p1, float& m_reg, float& mn, float& alpha) {
;     ...
;     for (int r = 0; r < 16; ++r) p0[r] = p0[r] - mn;
; #pragma unroll
;     for (int r = 0; r < 16; ++r) p1[r] = p1[r] - mn;
; __device__ __forceinline__ void finishSM(f32x16& p0, f32x16& p1, float alpha, float& l_reg, bf16x8& pa0, bf16x8& pa1, bf16x8& pa2, bf16x8& pa3) {
;     ...
;     l_reg = l_reg * alpha + ps;
.LBB0_578:
	v_cndmask_b32_e64 v144, v149, v144, s[2:3]
	v_pk_add_f32 v[80:81], v[80:81], v[144:145] op_sel_hi:[1,0] neg_lo:[0,1] neg_hi:[0,1]
	v_pk_add_f32 v[82:83], v[82:83], v[144:145] op_sel_hi:[1,0] neg_lo:[0,1] neg_hi:[0,1]
	v_pk_add_f32 v[84:85], v[84:85], v[144:145] op_sel_hi:[1,0] neg_lo:[0,1] neg_hi:[0,1]
	v_pk_add_f32 v[86:87], v[86:87], v[144:145] op_sel_hi:[1,0] neg_lo:[0,1] neg_hi:[0,1]
	v_pk_add_f32 v[88:89], v[88:89], v[144:145] op_sel_hi:[1,0] neg_lo:[0,1] neg_hi:[0,1]
	v_pk_add_f32 v[90:91], v[90:91], v[144:145] op_sel_hi:[1,0] neg_lo:[0,1] neg_hi:[0,1]
	v_pk_add_f32 v[92:93], v[92:93], v[144:145] op_sel_hi:[1,0] neg_lo:[0,1] neg_hi:[0,1]
	v_pk_add_f32 v[94:95], v[94:95], v[144:145] op_sel_hi:[1,0] neg_lo:[0,1] neg_hi:[0,1]
	v_exp_f32_e32 v178, v80
	v_exp_f32_e32 v211, v81
	v_exp_f32_e32 v208, v82
	v_exp_f32_e32 v210, v83
	v_exp_f32_e32 v206, v84
	v_exp_f32_e32 v209, v85
	v_exp_f32_e32 v205, v86
	v_exp_f32_e32 v207, v87
	v_exp_f32_e32 v202, v88
	v_exp_f32_e32 v204, v89
	v_exp_f32_e32 v200, v90
	v_exp_f32_e32 v203, v91
	v_exp_f32_e32 v198, v92
	v_exp_f32_e32 v201, v93
	v_exp_f32_e32 v179, v94
	v_exp_f32_e32 v199, v95
	v_pk_add_f32 v[158:159], v[64:65], v[144:145] op_sel_hi:[1,0] neg_lo:[0,1] neg_hi:[0,1]
	v_add_f32_e32 v64, v175, v176
	v_fmac_f32_e32 v64, v174, v172
	v_add_f32_e32 v172, v146, v147
	v_pk_add_f32 v[162:163], v[66:67], v[144:145] op_sel_hi:[1,0] neg_lo:[0,1] neg_hi:[0,1]
	v_pk_add_f32 v[166:167], v[68:69], v[144:145] op_sel_hi:[1,0] neg_lo:[0,1] neg_hi:[0,1]
	v_pk_add_f32 v[156:157], v[70:71], v[144:145] op_sel_hi:[1,0] neg_lo:[0,1] neg_hi:[0,1]
	v_pk_add_f32 v[160:161], v[72:73], v[144:145] op_sel_hi:[1,0] neg_lo:[0,1] neg_hi:[0,1]
	v_pk_add_f32 v[164:165], v[74:75], v[144:145] op_sel_hi:[1,0] neg_lo:[0,1] neg_hi:[0,1]
	v_pk_add_f32 v[168:169], v[76:77], v[144:145] op_sel_hi:[1,0] neg_lo:[0,1] neg_hi:[0,1]
	v_pk_add_f32 v[154:155], v[78:79], v[144:145] op_sel_hi:[1,0] neg_lo:[0,1] neg_hi:[0,1]
	v_fmac_f32_e32 v172, v64, v177
	v_add_u32_e32 v173, 0xffffff80, v173
	v_add_u32_e32 v197, 0x200, v197
	s_mov_b64 s[2:3], -1
	s_and_b64 vcc, exec, s[76:77]
	s_cbranch_vccz .LBB0_584
	s_and_b64 vcc, exec, s[66:67]
	s_cbranch_vccz .LBB0_581
	s_waitcnt vmcnt(0) lgkmcnt(0)
	s_barrier
	s_mov_b64 s[2:3], 0

; __device__ __forceinline__ void fox_block(const BlockRef& cur, const BlockRef& nxt, char* lds, Seam& S, const int tid) {
;     ...
;     for (int t = 1; t + 1 < NT; t += 2) {
;         STEP(pB0, pB1, mnB, alB, pA0, pA1, alA, t);
;         STEP(pA0, pA1, mnA, alA, pB0, pB1, alB, t + 1);
.LBB0_586:
	s_add_i32 s2, s92, 0x4000
	s_cmpk_lg_u32 s92, 0x8000
	s_cselect_b32 s3, s2, 0
	s_addk_i32 s91, 0x80
	s_add_u32 s82, s82, 0x8000
	s_addc_u32 s83, s83, 0
	s_add_i32 s87, s87, 2
	s_and_b64 vcc, exec, s[76:77]
	s_cbranch_vccnz .LBB0_588
	s_mov_b32 s2, s90
	s_mov_b32 s73, s72
	s_mov_b32 s90, s92
	s_mov_b32 s72, s3
	v_mov_b32_e32 v174, v148
	s_branch .LBB0_556
